# S2 + last-step peel + XCD-local GEMM->GEMM barriers; placement check now also requires the 256-workgroup grid
# baseline (speedup 1.0000x reference)
.LBB0_152:
	s_or_b64 exec, exec, s[0:1]
	s_ashr_i32 s3, s2, 31
	s_cmpk_gt_i32 s2, 0x8ff
	s_cselect_b64 s[96:97], -1, 0
	s_and_b64 s[0:1], s[96:97], exec
	s_movk_i32 s4, 0x200
	s_cselect_b32 s0, 0xfffff700, 0
	s_cselect_b32 s22, s4, 0x120
	s_movk_i32 s4, 0x100
	s_cselect_b32 s1, -1, 0
	s_cselect_b32 s19, 4, 64
	s_cselect_b32 s16, s4, 0x900
	s_add_u32 s0, s0, s2
	s_addc_u32 s1, s1, s3
	s_ashr_i32 s4, s0, 31
	s_lshr_b32 s4, s4, 29
	s_add_i32 s4, s0, s4
	s_ashr_i32 s25, s4, 3
	s_and_b32 s4, s4, -8
	v_readlane_b32 s40, v253, 0
	s_lshr_b32 s23, s16, 3
	s_sub_i32 s26, s0, s4
	s_ashr_i32 s33, s58, 31
	v_readlane_b32 s42, v253, 2
	v_readlane_b32 s43, v253, 3
	s_add_u32 s56, s42, 0x10200
	s_addc_u32 s57, s43, 0
	s_add_u32 s98, s42, 0x10400
	s_addc_u32 s99, s43, 0
	s_add_u32 s100, s42, 0x13700
	s_addc_u32 s101, s43, 0
	v_mov_b32_e32 v234, 0
	s_nop 3
	global_load_dwordx4 v[236:239], v234, s[100:101] sc1
	global_load_dwordx4 v[240:243], v234, s[100:101] offset:16 sc1
	s_waitcnt vmcnt(0)
	v_bcnt_u32_b32 v235, v236, 0
	v_bcnt_u32_b32 v235, v237, v235
	v_bcnt_u32_b32 v235, v238, v235
	v_bcnt_u32_b32 v235, v239, v235
	v_bcnt_u32_b32 v235, v240, v235
	v_bcnt_u32_b32 v235, v241, v235
	v_bcnt_u32_b32 v235, v242, v235
	v_bcnt_u32_b32 v235, v243, v235
	v_or3_b32 v244, v236, v237, v238
	v_or3_b32 v244, v244, v239, v240
	v_or3_b32 v244, v244, v241, v242
	v_or_b32_e32 v244, v244, v243
	v_bcnt_u32_b32 v244, v244, 0
	v_readfirstlane_b32 s100, v235
	v_readfirstlane_b32 s101, v244
	s_cmp_eq_u32 s100, 8
	s_cselect_b32 s100, 1, 0
	s_cmp_eq_u32 s101, 8
	s_cselect_b32 s100, s100, 0
	s_cmp_eq_u32 s58, 0x100
	s_cselect_b32 s100, s100, 0
	v_writelane_b32 v255, s100, 45
	s_add_u32 s4, s42, 0x10500
	s_addc_u32 s5, s43, 0
	s_add_u32 s6, s42, 0x10600
	s_addc_u32 s7, s43, 0
	s_add_u32 s8, s42, 0x10700
	s_addc_u32 s9, s43, 0
	v_readlane_b32 s41, v253, 1
	v_writelane_b32 v253, s8, 36
	v_cvt_f32_u32_e32 v0, s22
	v_mov_b32_e32 v1, 0
	v_writelane_b32 v253, s9, 37
	s_add_u32 s8, s42, 0x10800
	s_addc_u32 s9, s43, 0
	v_writelane_b32 v253, s8, 38
	v_rcp_iflag_f32_e32 v0, v0
	s_mul_i32 s59, s59, s58
	v_writelane_b32 v253, s9, 39
	s_add_u32 s8, s42, 0x10900
	s_addc_u32 s9, s43, 0
	v_writelane_b32 v253, s8, 40
	v_mul_f32_e32 v0, 0x4f7ffffe, v0
	v_cvt_u32_f32_e32 v0, v0
	v_writelane_b32 v253, s9, 41
	s_add_u32 s8, s42, 0x10a00
	s_addc_u32 s9, s43, 0
	v_writelane_b32 v253, s8, 42
	v_readfirstlane_b32 s35, v0
	v_mov_b64_e32 v[180:181], 0x100
	v_writelane_b32 v253, s9, 43
	s_add_u32 s8, s42, 0x10b00
	s_addc_u32 s9, s43, 0
	v_writelane_b32 v253, s8, 44
	s_mul_i32 s59, s59, s38
	v_mov_b32_e32 v211, 0x358637bd
	v_writelane_b32 v253, s9, 45
	s_add_u32 s8, s42, 0x10c00
	s_addc_u32 s9, s43, 0
	v_writelane_b32 v253, s8, 46
	v_mov_b32_e32 v252, 1
	v_mov_b64_e32 v[182:183], 0x8ff
	v_writelane_b32 v253, s9, 47
	s_add_u32 s8, s42, 0x10d00
	s_addc_u32 s9, s43, 0
	v_writelane_b32 v253, s8, 48
	v_mov_b32_e32 v216, 0x3e38aa3b
	v_mbcnt_hi_u32_b32 v217, -1, v12
	v_writelane_b32 v253, s9, 49
	s_add_u32 s8, s42, 0x10e00
	s_addc_u32 s9, s43, 0
	v_writelane_b32 v253, s8, 50
	v_mov_b32_e32 v218, 0x7f800000
	v_mov_b64_e32 v[184:185], 0xff
	v_writelane_b32 v253, s9, 51
	s_add_u32 s8, s42, 0x10f00
	s_addc_u32 s9, s43, 0
	v_writelane_b32 v253, s8, 52
	s_barrier
	s_nop 0
	v_writelane_b32 v253, s9, 53
	s_add_u32 s8, s42, 0x11000
	s_addc_u32 s9, s43, 0
	v_writelane_b32 v253, s8, 54
	s_nop 1
	v_writelane_b32 v253, s9, 55
	s_add_u32 s8, s42, 0x11100
	s_addc_u32 s9, s43, 0
	v_writelane_b32 v253, s8, 56
	s_nop 1
	v_writelane_b32 v253, s9, 57
	s_add_u32 s8, s42, 0x11200
	s_addc_u32 s9, s43, 0
	s_add_u32 s12, s42, 0x11300
	s_addc_u32 s13, s43, 0
	v_writelane_b32 v253, s8, 58
	s_cmp_eq_u32 s39, 15
	s_nop 0
	v_writelane_b32 v253, s9, 59
	s_cselect_b64 s[8:9], -1, 0
	v_writelane_b32 v253, s8, 60
	s_cmp_eq_u32 s39, 14
	s_nop 0
	v_writelane_b32 v253, s9, 61
	s_cselect_b64 s[8:9], -1, 0
	v_writelane_b32 v253, s8, 62
	s_cmp_eq_u32 s39, 13
	s_nop 0
	v_writelane_b32 v253, s9, 63
	s_cselect_b64 s[8:9], -1, 0
	v_writelane_b32 v254, s8, 0
	s_cmp_eq_u32 s39, 12
	s_nop 0
	v_writelane_b32 v254, s9, 1
	s_cselect_b64 s[8:9], -1, 0
	v_writelane_b32 v254, s8, 2
	s_cmp_eq_u32 s39, 11
	s_nop 0
	v_writelane_b32 v254, s9, 3
	s_cselect_b64 s[8:9], -1, 0
	v_writelane_b32 v254, s8, 4
	s_cmp_eq_u32 s39, 10
	s_nop 0
	v_writelane_b32 v254, s9, 5
	s_cselect_b64 s[8:9], -1, 0
	v_writelane_b32 v254, s8, 6
	s_cmp_eq_u32 s39, 9
	s_nop 0
	v_writelane_b32 v254, s9, 7
	s_cselect_b64 s[8:9], -1, 0
	v_writelane_b32 v254, s8, 8
	s_cmp_eq_u32 s39, 8
	s_nop 0
	v_writelane_b32 v254, s9, 9
	s_cselect_b64 s[8:9], -1, 0
	v_writelane_b32 v254, s8, 10
	s_cmp_eq_u32 s39, 7
	s_nop 0
	v_writelane_b32 v254, s9, 11
	s_cselect_b64 s[8:9], -1, 0
	v_writelane_b32 v254, s8, 12
	s_cmp_eq_u32 s39, 6
	s_nop 0
	v_writelane_b32 v254, s9, 13
	s_cselect_b64 s[8:9], -1, 0
	v_writelane_b32 v254, s8, 14
	s_cmp_eq_u32 s39, 5
	s_nop 0
	v_writelane_b32 v254, s9, 15
	s_cselect_b64 s[8:9], -1, 0
	v_writelane_b32 v254, s8, 16
	s_cmp_eq_u32 s39, 4
	s_nop 0
	v_writelane_b32 v254, s9, 17
	s_cselect_b64 s[8:9], -1, 0
	v_writelane_b32 v254, s8, 18
	s_cmp_eq_u32 s39, 3
	s_nop 0
	v_writelane_b32 v254, s9, 19
	s_cselect_b64 s[8:9], -1, 0
	v_writelane_b32 v254, s8, 20
	s_cmp_eq_u32 s39, 2
	s_nop 0
	v_writelane_b32 v254, s9, 21
	s_cselect_b64 s[8:9], -1, 0
	v_writelane_b32 v254, s8, 22
	s_cmp_eq_u32 s39, 1
	s_nop 0
	v_writelane_b32 v254, s9, 23
	s_cselect_b64 s[8:9], -1, 0
	v_writelane_b32 v254, s8, 24
	s_cmp_eq_u32 s39, 0
	s_nop 0
	v_writelane_b32 v254, s9, 25
	s_cselect_b64 s[8:9], -1, 0
	s_lshl_b32 s17, s39, 8
	s_add_u32 s14, s14, s17
	v_writelane_b32 v254, s8, 26
	s_addc_u32 s15, s15, 0
	s_mov_b64 s[38:39], s[6:7]
	v_writelane_b32 v254, s9, 27
	s_add_u32 s8, s14, 0x1400
	s_addc_u32 s9, s15, 0
	v_writelane_b32 v254, s8, 28
	s_nop 1
	v_writelane_b32 v254, s9, 29
	s_add_u32 s8, s14, 0x2400
	s_addc_u32 s9, s15, 0
	v_writelane_b32 v254, s8, 30
	s_nop 1
	v_writelane_b32 v254, s9, 31
	s_add_u32 s8, s42, 0x13400
	s_addc_u32 s9, s43, 0
	v_writelane_b32 v254, s8, 32
	s_nop 1
	v_writelane_b32 v254, s9, 33
	s_add_u32 s8, s42, 0x13500
	s_addc_u32 s9, s43, 0
	v_writelane_b32 v254, s8, 34
	s_add_i32 s14, s58, 7
	s_ashr_i32 s64, s14, 3
	v_writelane_b32 v254, s9, 35
	s_lshl_b32 s8, s2, 9
	s_lshl_b32 s93, s58, 9
	s_and_b32 s24, s2, 7
	s_ashr_i32 s55, s2, 3
	s_cmp_lt_i32 s55, 32
	s_cselect_b64 s[20:21], -1, 0
	s_lshl_b32 s14, s55, 1
	s_and_b32 s14, s14, 62
	s_lshl_b32 s17, s14, 16
	s_lshl_b32 s34, s14, 6
	s_lshl_b32 s67, s24, 7
	s_or_b32 s18, s17, 0x10000
	s_or_b32 s65, s34, 63
	s_cmpk_gt_i32 s2, 0xff
	v_writelane_b32 v254, s8, 36
	s_cselect_b64 s[8:9], -1, 0
	v_writelane_b32 v254, s8, 37
	s_and_b64 s[14:15], s[8:9], exec
	s_cselect_b32 s14, 0xffffff00, 0
	s_cselect_b32 s15, -1, 0
	s_add_u32 s14, s14, s2
	s_addc_u32 s15, s15, s3
	s_ashr_i32 s27, s14, 31
	s_lshr_b32 s27, s27, 29
	s_add_i32 s27, s14, s27
	s_ashr_i32 s28, s27, 3
	s_and_b32 s27, s27, -8
	s_sub_i32 s27, s14, s27
	s_lshl_b32 s29, s27, 5
	s_cmpk_lt_i32 s2, 0x100
	v_writelane_b32 v254, s9, 38
	s_cselect_b64 s[8:9], -1, 0
	s_lshr_b32 s30, s26, 31
	s_or_b32 s23, s23, s30
	s_mul_i32 s23, s26, s23
	s_add_i32 s23, s23, s25
	s_lshr_b32 s25, s3, 29
	s_add_i32 s25, s2, s25
	s_ashr_i32 s26, s25, 3
	s_and_b32 s25, s25, -8
	s_sub_i32 s25, s2, s25
	s_lshl_b32 s30, s25, 5
	s_cmp_lt_i32 s27, 0
	s_mul_i32 s27, s27, 33
	s_cselect_b32 s27, s27, s29
	s_add_i32 s27, s27, s28
	s_ashr_i32 s28, s27, 31
	s_lshr_b32 s28, s28, 27
	s_add_i32 s28, s27, s28
	s_and_b32 s29, s28, 0xffffffe0
	s_sub_i32 s29, s27, s29
	s_ashr_i32 s27, s28, 5
	s_lshl_b32 s28, s27, 3
	s_sub_i32 s27, 64, s28
	s_min_i32 s31, s27, 8
	s_cmp_lt_i32 s25, 0
	s_mul_i32 s25, s25, 33
	s_cselect_b32 s25, s25, s30
	s_add_i32 s25, s25, s26
	s_ashr_i32 s26, s25, 31
	s_lshr_b32 s26, s26, 27
	s_add_i32 s26, s25, s26
	s_and_b32 s27, s26, 0xffe0
	s_sub_i32 s25, s25, s27
	s_bfe_i32 s27, s25, 0x80000
	s_bfe_u32 s27, s27, 0x3000c
	s_add_i32 s27, s25, s27
	s_and_b32 s30, s27, 0xf8
	s_sub_i32 s25, s25, s30
	s_ashr_i32 s26, s26, 5
	s_bfe_i32 s27, s27, 0x80000
	s_sub_i32 s30, 0, s22
	s_lshl_b32 s26, s26, 3
	s_sext_i32_i16 s27, s27
	s_sext_i32_i8 s25, s25
	v_writelane_b32 v254, s8, 39
	s_mul_i32 s30, s30, s35
	s_add_i32 s10, s26, s25
	s_lshr_b32 s26, s27, 3
	v_writelane_b32 v254, s9, 40
	s_mul_hi_u32 s30, s35, s30
	s_ashr_i32 s8, s27, 3
	s_bfe_i64 s[26:27], s[26:27], 0x100000
	s_add_i32 s35, s35, s30
	s_abs_i32 s30, s23
	v_writelane_b32 v254, s8, 41
	s_lshl_b64 s[8:9], s[26:27], 19
	s_mul_hi_u32 s35, s30, s35
	v_writelane_b32 v254, s8, 42
	s_mul_i32 s36, s35, s22
	s_sub_i32 s30, s30, s36
	v_writelane_b32 v254, s9, 43
	s_mov_b32 s8, s10
	s_ashr_i32 s11, s10, 31
	v_writelane_b32 v254, s8, 44
	s_ashr_i32 s25, s23, 31
	s_add_i32 s26, s35, 1
	s_sub_i32 s27, s30, s22
	v_writelane_b32 v254, s9, 45
	s_lshl_b64 s[8:9], s[10:11], 19
	s_cmp_ge_u32 s30, s22
	s_cselect_b32 s26, s26, s35
	s_cselect_b32 s27, s27, s30
	s_add_i32 s30, s26, 1
	s_cmp_ge_u32 s27, s22
	s_cselect_b32 s26, s30, s26
	s_xor_b32 s26, s26, s25
	s_sub_i32 s25, s26, s25
	s_mul_i32 s22, s25, s22
	s_sub_i32 s22, s23, s22
	s_lshl_b32 s23, s25, 3
	s_sub_i32 s19, s19, s23
	s_min_i32 s19, s19, 8
	s_abs_i32 s25, s19
	v_cvt_f32_u32_e32 v0, s25
	s_sub_i32 s26, 0, s25
	v_writelane_b32 v254, s8, 46
	v_cmp_lt_i64_e64 s[6:7], s[14:15], v[180:181]
	v_rcp_iflag_f32_e32 v0, v0
	v_writelane_b32 v254, s9, 47
	v_mul_f32_e32 v0, 0x4f7ffffe, v0
	v_cvt_u32_f32_e32 v0, v0
	s_nop 0
	v_readfirstlane_b32 s27, v0
	s_mul_i32 s26, s26, s27
	s_mul_hi_u32 s26, s27, s26
	s_add_i32 s27, s27, s26
	s_abs_i32 s26, s22
	s_mul_hi_u32 s27, s26, s27
	s_mul_i32 s30, s27, s25
	s_sub_i32 s26, s26, s30
	s_xor_b32 s30, s22, s19
	s_ashr_i32 s30, s30, 31
	s_add_i32 s35, s27, 1
	s_sub_i32 s36, s26, s25
	s_cmp_ge_u32 s26, s25
	s_cselect_b32 s27, s35, s27
	s_cselect_b32 s26, s36, s26
	s_add_i32 s35, s27, 1
	s_cmp_ge_u32 s26, s25
	s_cselect_b32 s25, s35, s27
	s_xor_b32 s25, s25, s30
	s_sub_i32 s8, s25, s30
	s_mul_i32 s19, s8, s19
	s_sub_i32 s19, s22, s19
	v_writelane_b32 v254, s8, 48
	s_add_i32 s8, s19, s23
	s_abs_i32 s19, s31
	v_cvt_f32_u32_e32 v0, s19
	s_sub_i32 s22, 0, s19
	v_writelane_b32 v254, s8, 49
	v_rcp_iflag_f32_e32 v0, v0
	s_nop 0
	v_mul_f32_e32 v0, 0x4f7ffffe, v0
	v_cvt_u32_f32_e32 v0, v0
	s_nop 0
	v_readfirstlane_b32 s23, v0
	s_mul_i32 s22, s22, s23
	s_mul_hi_u32 s22, s23, s22
	s_add_i32 s23, s23, s22
	s_abs_i32 s22, s29
	s_mul_hi_u32 s23, s22, s23
	s_mul_i32 s25, s23, s19
	s_sub_i32 s22, s22, s25
	s_xor_b32 s25, s29, s31
	s_ashr_i32 s25, s25, 31
	s_add_i32 s26, s23, 1
	s_sub_i32 s27, s22, s19
	s_cmp_ge_u32 s22, s19
	s_cselect_b32 s23, s26, s23
	v_mov_b32_e32 v0, s16
	s_cselect_b32 s22, s27, s22
	s_add_i32 s26, s23, 1
	v_cmp_lt_i64_e64 s[0:1], s[0:1], v[0:1]
	s_cmp_ge_u32 s22, s19
	s_nop 0
	v_writelane_b32 v254, s0, 50
	s_nop 1
	v_writelane_b32 v254, s1, 51
	v_cndmask_b32_e64 v179, 0, 1, s[0:1]
	s_cselect_b32 s0, s26, s23
	s_xor_b32 s0, s0, s25
	s_sub_i32 s8, s0, s25
	s_mul_i32 s0, s8, s31
	v_writelane_b32 v254, s6, 52
	s_sub_i32 s0, s29, s0
	s_lshl_b32 s1, s2, 12
	v_writelane_b32 v254, s7, 53
	s_add_i32 s10, s28, s0
	v_writelane_b32 v254, s1, 54
	s_lshl_b32 s1, s58, 12
	v_writelane_b32 v254, s1, 55
	s_mov_b32 s6, s10
	s_ashr_i32 s11, s10, 31
	v_writelane_b32 v254, s6, 56
	s_ashr_i32 s9, s8, 31
	s_mul_i32 s0, s24, 0x280
	v_writelane_b32 v254, s7, 57
	s_lshl_b64 s[6:7], s[10:11], 19
	v_writelane_b32 v254, s6, 58
	s_mulk_i32 s24, 0xa00
	s_mov_b32 s23, 0
	v_writelane_b32 v254, s7, 59
	s_mov_b32 s6, s8
	v_writelane_b32 v254, s6, 60
	s_mov_b32 s35, s23
	s_mov_b64 s[10:11], 0x80
	v_writelane_b32 v254, s7, 61
	s_lshl_b64 s[6:7], s[8:9], 19
	s_add_u32 s1, s42, s24
	s_addc_u32 s14, s43, 0
	s_add_u32 s1, s1, 0x100
	v_writelane_b32 v255, s1, 0
	s_addc_u32 s1, s14, 0
	v_writelane_b32 v255, s1, 1
	s_lshl_b32 s0, s0, 2
	v_writelane_b32 v255, s0, 2
	s_add_i32 s0, 0, 0x20140
	v_writelane_b32 v255, s0, 3
	s_add_i32 s0, 0, 0x20144
	v_writelane_b32 v255, s0, 4
	v_writelane_b32 v255, s94, 5
	s_and_b32 s1, s55, 31
	v_writelane_b32 v254, s6, 62
	v_writelane_b32 v255, s95, 6
	v_writelane_b32 v255, s4, 7
	s_lshl_b32 s82, s1, 17
	v_writelane_b32 v254, s7, 63
	v_writelane_b32 v255, s5, 8
	v_writelane_b32 v255, s38, 9
	s_lshl_b32 s66, s1, 7
	s_add_i32 s82, s82, 0x30000
	v_writelane_b32 v255, s39, 10
	v_writelane_b32 v255, s93, 11
	v_writelane_b32 v255, s56, 12
	s_add_i32 s83, 0, 0x11800
	s_add_i32 s68, 0, 0x11000
	v_writelane_b32 v255, s57, 13
	v_writelane_b32 v255, s98, 14
	s_lshl_b32 s28, s17, 1
	s_lshl_b32 s30, s18, 1
	v_writelane_b32 v255, s99, 15
	v_writelane_b32 v255, s96, 16
	s_mov_b32 s6, 0
	s_nop 0
	v_writelane_b32 v255, s97, 17
	s_branch .LBB0_154
